# gate/up GEMM epilogue: the 8 row-group loads of the partial sums of squares requested together at the start of the epilogue (into dead B-fragment registers) and waited once, instead of one load -> vmc
# baseline (speedup 1.0000x reference)
.LBB0_2656:
	v_lshl_add_u32 v150, s0, 8, v154
	v_ashrrev_i32_e32 v151, 31, v150
	v_lshlrev_b64 v[148:149], 6, v[150:151]
	v_lshl_add_u64 v[148:149], v[138:139], 0, v[148:149]
	global_load_dwordx4 v[188:191], v[148:149], off
	global_load_dwordx4 v[192:195], v[148:149], off offset:1024
	global_load_dwordx4 v[196:199], v[148:149], off offset:2048
	global_load_dwordx4 v[204:207], v[148:149], off offset:3072
	v_add_co_u32_e32 v162, vcc, 0x2000, v148
	s_nop 1
	v_addc_co_u32_e32 v163, vcc, 0, v149, vcc
	global_load_dwordx4 v[208:211], v[162:163], off
	global_load_dwordx4 v[212:215], v[162:163], off offset:1024
	global_load_dwordx4 v[216:219], v[162:163], off offset:2048
	global_load_dwordx4 v[220:223], v[162:163], off offset:3072
	s_lshl_b32 s0, s1, 7
	v_mov_b64_e32 v[148:149], s[8:9]
	s_ashr_i32 s1, s0, 31
	v_mad_i64_i32 v[164:165], s[24:25], v150, s50, v[148:149]
	s_lshl_b64 s[24:25], s[0:1], 1
	s_nop 0
	v_lshl_add_u64 v[164:165], v[164:165], 0, s[24:25]
	v_or_b32_e32 v166, 16, v150
	v_ashrrev_i32_e32 v167, 31, v166
	v_lshlrev_b64 v[168:169], 6, v[166:167]
	s_waitcnt vmcnt(0)
	v_add_f32_e32 v151, v188, v189
	v_add_f32_e32 v160, v190, v191
	v_add_f32_e32 v151, v151, v160
	v_mov_b32_e32 v160, v151
	s_nop 1
	v_permlane16_swap_b32_e32 v151, v160
	v_add_f32_e32 v151, v151, v160
	v_mov_b32_e32 v160, v151
	s_nop 1
	v_permlane32_swap_b32_e32 v151, v160
	v_add_f32_e32 v151, v151, v160
	v_fmamk_f32 v151, v151, 0x3a800000, v159
	v_mul_f32_e32 v160, 0x4b800000, v151
	v_cmp_gt_f32_e32 vcc, s49, v151
	v_lshl_add_u64 v[162:163], v[138:139], 0, v[168:169]
	s_nop 0
	v_cndmask_b32_e32 v151, v151, v160, vcc
	v_rsq_f32_e32 v151, v151
	v_lshl_add_u64 v[160:161], v[164:165], 0, s[12:13]
	v_lshl_add_u64 v[160:161], v[160:161], 0, v[136:137]
	v_mul_f32_e32 v164, 0x45800000, v151
	v_cndmask_b32_e32 v164, v151, v164, vcc
	v_pk_mul_f32 v[126:127], v[126:127], v[164:165] op_sel_hi:[1,0]
	v_pk_mul_f32 v[124:125], v[124:125], v[164:165] op_sel_hi:[1,0]
	v_pk_mul_f32 v[122:123], v[122:123], v[164:165] op_sel_hi:[1,0]
	v_pk_mul_f32 v[120:121], v[120:121], v[164:165] op_sel_hi:[1,0]
	v_pk_mul_f32 v[118:119], v[118:119], v[164:165] op_sel_hi:[1,0]
	v_pk_mul_f32 v[116:117], v[116:117], v[164:165] op_sel_hi:[1,0]
	v_pk_mul_f32 v[114:115], v[114:115], v[164:165] op_sel_hi:[1,0]
	v_pk_mul_f32 v[112:113], v[112:113], v[164:165] op_sel_hi:[1,0]
	v_mul_f32_e32 v151, 0xbfb8aa3b, v124
	v_mul_f32_e32 v164, 0xbfb8aa3b, v125
	v_mul_f32_e32 v165, 0xbfb8aa3b, v126
	v_mul_f32_e32 v167, 0xbfb8aa3b, v127
	v_mul_f32_e32 v168, 0xbfb8aa3b, v120
	v_mul_f32_e32 v169, 0xbfb8aa3b, v121
	v_mul_f32_e32 v170, 0xbfb8aa3b, v122
	v_mul_f32_e32 v171, 0xbfb8aa3b, v123
	v_exp_f32_e32 v151, v151
	v_exp_f32_e32 v164, v164
	v_exp_f32_e32 v165, v165
	v_exp_f32_e32 v167, v167
	v_exp_f32_e32 v168, v168
	v_exp_f32_e32 v169, v169
	v_exp_f32_e32 v170, v170
	v_exp_f32_e32 v171, v171
	v_add_f32_e32 v151, 1.0, v151
	v_add_f32_e32 v172, 1.0, v164
	v_add_f32_e32 v173, 1.0, v165
	v_add_f32_e32 v167, 1.0, v167
	v_add_f32_e32 v174, 1.0, v168
	v_add_f32_e32 v175, 1.0, v169
	v_add_f32_e32 v176, 1.0, v170
	v_add_f32_e32 v177, 1.0, v171
	v_rcp_f32_e32 v164, v151
	v_rcp_f32_e32 v165, v172
	v_rcp_f32_e32 v168, v173
	v_rcp_f32_e32 v169, v167
	v_rcp_f32_e32 v170, v174
	v_rcp_f32_e32 v171, v175
	v_rcp_f32_e32 v172, v176
	v_rcp_f32_e32 v173, v177
	v_pk_mul_f32 v[124:125], v[124:125], v[164:165]
	v_pk_mul_f32 v[126:127], v[126:127], v[168:169]
	v_pk_mul_f32 v[120:121], v[120:121], v[170:171]
	v_pk_mul_f32 v[122:123], v[122:123], v[172:173]
	v_pk_mul_f32 v[116:117], v[116:117], v[124:125]
	v_pk_mul_f32 v[118:119], v[118:119], v[126:127]
	v_pk_mul_f32 v[120:121], v[112:113], v[120:121]
	v_pk_mul_f32 v[122:123], v[114:115], v[122:123]
	v_cvt_pk_bf16_f32 v112, v116, v117
	v_cvt_pk_bf16_f32 v113, v118, v119
	v_cvt_pk_bf16_f32 v114, v120, v121
	v_cvt_pk_bf16_f32 v115, v122, v123
	global_store_dwordx4 v[160:161], v[112:115], off
	v_or_b32_e32 v116, 32, v150
	v_ashrrev_i32_e32 v117, 31, v116
	v_lshlrev_b64 v[120:121], 6, v[116:117]
	v_mad_i64_i32 v[118:119], s[0:1], v166, s50, v[148:149]
	v_lshl_add_u64 v[118:119], v[118:119], 0, s[24:25]
	v_add_f32_e32 v112, v192, v193
	v_add_f32_e32 v113, v194, v195
	v_add_f32_e32 v112, v112, v113
	v_mov_b32_e32 v113, v112
	s_nop 1
	v_permlane16_swap_b32_e32 v112, v113
	v_add_f32_e32 v112, v112, v113
	v_mov_b32_e32 v113, v112
	s_nop 1
	v_permlane32_swap_b32_e32 v112, v113
	v_add_f32_e32 v112, v112, v113
	v_fmamk_f32 v112, v112, 0x3a800000, v159
	v_mul_f32_e32 v113, 0x4b800000, v112
	v_cmp_gt_f32_e32 vcc, s49, v112
	v_lshl_add_u64 v[114:115], v[138:139], 0, v[120:121]
	s_nop 0
	v_cndmask_b32_e32 v112, v112, v113, vcc
	v_rsq_f32_e32 v117, v112
	v_lshl_add_u64 v[112:113], v[118:119], 0, s[12:13]
	v_lshl_add_u64 v[112:113], v[112:113], 0, v[136:137]
	v_mul_f32_e32 v118, 0x45800000, v117
	v_cndmask_b32_e32 v118, v117, v118, vcc
	v_pk_mul_f32 v[110:111], v[110:111], v[118:119] op_sel_hi:[1,0]
	v_pk_mul_f32 v[108:109], v[108:109], v[118:119] op_sel_hi:[1,0]
	v_pk_mul_f32 v[106:107], v[106:107], v[118:119] op_sel_hi:[1,0]
	v_pk_mul_f32 v[104:105], v[104:105], v[118:119] op_sel_hi:[1,0]
	v_pk_mul_f32 v[102:103], v[102:103], v[118:119] op_sel_hi:[1,0]
	v_pk_mul_f32 v[100:101], v[100:101], v[118:119] op_sel_hi:[1,0]
	v_pk_mul_f32 v[98:99], v[98:99], v[118:119] op_sel_hi:[1,0]
	v_pk_mul_f32 v[96:97], v[96:97], v[118:119] op_sel_hi:[1,0]
	v_mul_f32_e32 v117, 0xbfb8aa3b, v108
	v_mul_f32_e32 v118, 0xbfb8aa3b, v109
	v_mul_f32_e32 v119, 0xbfb8aa3b, v110
	v_mul_f32_e32 v120, 0xbfb8aa3b, v111
	v_mul_f32_e32 v121, 0xbfb8aa3b, v104
	v_mul_f32_e32 v122, 0xbfb8aa3b, v105
	v_mul_f32_e32 v123, 0xbfb8aa3b, v106
	v_mul_f32_e32 v124, 0xbfb8aa3b, v107
	v_exp_f32_e32 v117, v117
	v_exp_f32_e32 v118, v118
	v_exp_f32_e32 v119, v119
	v_exp_f32_e32 v120, v120
	v_exp_f32_e32 v121, v121
	v_exp_f32_e32 v122, v122
	v_exp_f32_e32 v123, v123
	v_exp_f32_e32 v124, v124
	v_add_f32_e32 v117, 1.0, v117
	v_add_f32_e32 v125, 1.0, v118
	v_add_f32_e32 v126, 1.0, v119
	v_add_f32_e32 v127, 1.0, v120
	v_add_f32_e32 v151, 1.0, v121
	v_add_f32_e32 v160, 1.0, v122
	v_add_f32_e32 v161, 1.0, v123
	v_add_f32_e32 v162, 1.0, v124
	v_rcp_f32_e32 v118, v117
	v_rcp_f32_e32 v119, v125
	v_rcp_f32_e32 v120, v126
	v_rcp_f32_e32 v121, v127
	v_rcp_f32_e32 v122, v151
	v_rcp_f32_e32 v123, v160
	v_rcp_f32_e32 v124, v161
	v_rcp_f32_e32 v125, v162
	v_pk_mul_f32 v[108:109], v[108:109], v[118:119]
	v_pk_mul_f32 v[110:111], v[110:111], v[120:121]
	v_pk_mul_f32 v[104:105], v[104:105], v[122:123]
	v_pk_mul_f32 v[106:107], v[106:107], v[124:125]
	v_pk_mul_f32 v[100:101], v[100:101], v[108:109]
	v_pk_mul_f32 v[102:103], v[102:103], v[110:111]
	v_pk_mul_f32 v[104:105], v[96:97], v[104:105]
	v_pk_mul_f32 v[106:107], v[98:99], v[106:107]
	v_cvt_pk_bf16_f32 v96, v100, v101
	v_cvt_pk_bf16_f32 v97, v102, v103
	v_cvt_pk_bf16_f32 v98, v104, v105
	v_cvt_pk_bf16_f32 v99, v106, v107
	global_store_dwordx4 v[112:113], v[96:99], off
	v_or_b32_e32 v100, 48, v150
	v_ashrrev_i32_e32 v101, 31, v100
	v_lshlrev_b64 v[104:105], 6, v[100:101]
	v_mad_i64_i32 v[102:103], s[0:1], v116, s50, v[148:149]
	v_lshl_add_u64 v[102:103], v[102:103], 0, s[24:25]
	v_add_f32_e32 v96, v196, v197
	v_add_f32_e32 v97, v198, v199
	v_add_f32_e32 v96, v96, v97
	v_mov_b32_e32 v97, v96
	s_nop 1
	v_permlane16_swap_b32_e32 v96, v97
	v_add_f32_e32 v96, v96, v97
	v_mov_b32_e32 v97, v96
	s_nop 1
	v_permlane32_swap_b32_e32 v96, v97
	v_add_f32_e32 v96, v96, v97
	v_fmamk_f32 v96, v96, 0x3a800000, v159
	v_mul_f32_e32 v97, 0x4b800000, v96
	v_cmp_gt_f32_e32 vcc, s49, v96
	v_lshl_add_u64 v[98:99], v[138:139], 0, v[104:105]
	s_nop 0
	v_cndmask_b32_e32 v96, v96, v97, vcc
	v_rsq_f32_e32 v101, v96
	v_lshl_add_u64 v[96:97], v[102:103], 0, s[12:13]
	v_lshl_add_u64 v[96:97], v[96:97], 0, v[136:137]
	v_mul_f32_e32 v102, 0x45800000, v101
	v_cndmask_b32_e32 v102, v101, v102, vcc
	v_pk_mul_f32 v[94:95], v[94:95], v[102:103] op_sel_hi:[1,0]
	v_pk_mul_f32 v[92:93], v[92:93], v[102:103] op_sel_hi:[1,0]
	v_pk_mul_f32 v[90:91], v[90:91], v[102:103] op_sel_hi:[1,0]
	v_pk_mul_f32 v[88:89], v[88:89], v[102:103] op_sel_hi:[1,0]
	v_pk_mul_f32 v[86:87], v[86:87], v[102:103] op_sel_hi:[1,0]
	v_pk_mul_f32 v[84:85], v[84:85], v[102:103] op_sel_hi:[1,0]
	v_pk_mul_f32 v[82:83], v[82:83], v[102:103] op_sel_hi:[1,0]
	v_pk_mul_f32 v[80:81], v[80:81], v[102:103] op_sel_hi:[1,0]
	v_mul_f32_e32 v101, 0xbfb8aa3b, v92
	v_mul_f32_e32 v102, 0xbfb8aa3b, v93
	v_mul_f32_e32 v103, 0xbfb8aa3b, v94
	v_mul_f32_e32 v104, 0xbfb8aa3b, v95
	v_mul_f32_e32 v105, 0xbfb8aa3b, v88
	v_mul_f32_e32 v106, 0xbfb8aa3b, v89
	v_mul_f32_e32 v107, 0xbfb8aa3b, v90
	v_mul_f32_e32 v108, 0xbfb8aa3b, v91
	v_exp_f32_e32 v101, v101
	v_exp_f32_e32 v102, v102
	v_exp_f32_e32 v103, v103
	v_exp_f32_e32 v104, v104
	v_exp_f32_e32 v105, v105
	v_exp_f32_e32 v106, v106
	v_exp_f32_e32 v107, v107
	v_exp_f32_e32 v108, v108
	v_add_f32_e32 v101, 1.0, v101
	v_add_f32_e32 v109, 1.0, v102
	v_add_f32_e32 v110, 1.0, v103
	v_add_f32_e32 v111, 1.0, v104
	v_add_f32_e32 v112, 1.0, v105
	v_add_f32_e32 v113, 1.0, v106
	v_add_f32_e32 v114, 1.0, v107
	v_add_f32_e32 v115, 1.0, v108
	v_rcp_f32_e32 v102, v101
	v_rcp_f32_e32 v103, v109
	v_rcp_f32_e32 v104, v110
	v_rcp_f32_e32 v105, v111
	v_rcp_f32_e32 v106, v112
	v_rcp_f32_e32 v107, v113
	v_rcp_f32_e32 v108, v114
	v_rcp_f32_e32 v109, v115
	v_pk_mul_f32 v[92:93], v[92:93], v[102:103]
	v_pk_mul_f32 v[94:95], v[94:95], v[104:105]
	v_pk_mul_f32 v[88:89], v[88:89], v[106:107]
	v_pk_mul_f32 v[90:91], v[90:91], v[108:109]
	v_pk_mul_f32 v[84:85], v[84:85], v[92:93]
	v_pk_mul_f32 v[86:87], v[86:87], v[94:95]
	v_pk_mul_f32 v[88:89], v[80:81], v[88:89]
	v_pk_mul_f32 v[90:91], v[82:83], v[90:91]
	v_cvt_pk_bf16_f32 v80, v84, v85
	v_cvt_pk_bf16_f32 v81, v86, v87
	v_cvt_pk_bf16_f32 v82, v88, v89
	v_cvt_pk_bf16_f32 v83, v90, v91
	global_store_dwordx4 v[96:97], v[80:83], off
	v_add_u32_e32 v84, 0x80, v150
	v_ashrrev_i32_e32 v85, 31, v84
	v_lshlrev_b64 v[88:89], 6, v[84:85]
	v_mad_i64_i32 v[86:87], s[0:1], v100, s50, v[148:149]
	v_lshl_add_u64 v[86:87], v[86:87], 0, s[24:25]
	v_add_f32_e32 v80, v204, v205
	v_add_f32_e32 v81, v206, v207
	v_add_f32_e32 v80, v80, v81
	v_mov_b32_e32 v81, v80
	s_nop 1
	v_permlane16_swap_b32_e32 v80, v81
	v_add_f32_e32 v80, v80, v81
	v_mov_b32_e32 v81, v80
	s_nop 1
	v_permlane32_swap_b32_e32 v80, v81
	v_add_f32_e32 v80, v80, v81
	v_fmamk_f32 v80, v80, 0x3a800000, v159
	v_mul_f32_e32 v81, 0x4b800000, v80
	v_cmp_gt_f32_e32 vcc, s49, v80
	v_lshl_add_u64 v[82:83], v[138:139], 0, v[88:89]
	s_nop 0
	v_cndmask_b32_e32 v80, v80, v81, vcc
	v_rsq_f32_e32 v85, v80
	v_lshl_add_u64 v[80:81], v[86:87], 0, s[12:13]
	v_lshl_add_u64 v[80:81], v[80:81], 0, v[136:137]
	v_mul_f32_e32 v86, 0x45800000, v85
	v_cndmask_b32_e32 v86, v85, v86, vcc
	v_pk_mul_f32 v[78:79], v[78:79], v[86:87] op_sel_hi:[1,0]
	v_pk_mul_f32 v[76:77], v[76:77], v[86:87] op_sel_hi:[1,0]
	v_pk_mul_f32 v[74:75], v[74:75], v[86:87] op_sel_hi:[1,0]
	v_pk_mul_f32 v[72:73], v[72:73], v[86:87] op_sel_hi:[1,0]
	v_pk_mul_f32 v[70:71], v[70:71], v[86:87] op_sel_hi:[1,0]
	v_pk_mul_f32 v[68:69], v[68:69], v[86:87] op_sel_hi:[1,0]
	v_pk_mul_f32 v[66:67], v[66:67], v[86:87] op_sel_hi:[1,0]
	v_pk_mul_f32 v[64:65], v[64:65], v[86:87] op_sel_hi:[1,0]
	v_mul_f32_e32 v85, 0xbfb8aa3b, v76
	v_mul_f32_e32 v86, 0xbfb8aa3b, v77
	v_mul_f32_e32 v87, 0xbfb8aa3b, v78
	v_mul_f32_e32 v88, 0xbfb8aa3b, v79
	v_mul_f32_e32 v89, 0xbfb8aa3b, v72
	v_mul_f32_e32 v90, 0xbfb8aa3b, v73
	v_mul_f32_e32 v91, 0xbfb8aa3b, v74
	v_mul_f32_e32 v92, 0xbfb8aa3b, v75
	v_exp_f32_e32 v85, v85
	v_exp_f32_e32 v86, v86
	v_exp_f32_e32 v87, v87
	v_exp_f32_e32 v88, v88
	v_exp_f32_e32 v89, v89
	v_exp_f32_e32 v90, v90
	v_exp_f32_e32 v91, v91
	v_exp_f32_e32 v92, v92
	v_add_f32_e32 v85, 1.0, v85
	v_add_f32_e32 v93, 1.0, v86
	v_add_f32_e32 v94, 1.0, v87
	v_add_f32_e32 v95, 1.0, v88
	v_add_f32_e32 v96, 1.0, v89
	v_add_f32_e32 v97, 1.0, v90
	v_add_f32_e32 v98, 1.0, v91
	v_add_f32_e32 v99, 1.0, v92
	v_rcp_f32_e32 v86, v85
	v_rcp_f32_e32 v87, v93
	v_rcp_f32_e32 v88, v94
	v_rcp_f32_e32 v89, v95
	v_rcp_f32_e32 v90, v96
	v_rcp_f32_e32 v91, v97
	v_rcp_f32_e32 v92, v98
	v_rcp_f32_e32 v93, v99
	v_pk_mul_f32 v[76:77], v[76:77], v[86:87]
	v_pk_mul_f32 v[78:79], v[78:79], v[88:89]
	v_pk_mul_f32 v[72:73], v[72:73], v[90:91]
	v_pk_mul_f32 v[74:75], v[74:75], v[92:93]
	v_pk_mul_f32 v[68:69], v[68:69], v[76:77]
	v_pk_mul_f32 v[70:71], v[70:71], v[78:79]
	v_pk_mul_f32 v[72:73], v[64:65], v[72:73]
	v_pk_mul_f32 v[74:75], v[66:67], v[74:75]
	v_cvt_pk_bf16_f32 v64, v68, v69
	v_cvt_pk_bf16_f32 v65, v70, v71
	v_cvt_pk_bf16_f32 v66, v72, v73
	v_cvt_pk_bf16_f32 v67, v74, v75
	global_store_dwordx4 v[80:81], v[64:67], off
	v_add_u32_e32 v68, 0x90, v150
	v_ashrrev_i32_e32 v69, 31, v68
	v_lshlrev_b64 v[72:73], 6, v[68:69]
	v_mad_i64_i32 v[70:71], s[0:1], v84, s50, v[148:149]
	v_lshl_add_u64 v[70:71], v[70:71], 0, s[24:25]
	v_add_f32_e32 v64, v208, v209
	v_add_f32_e32 v65, v210, v211
	v_add_f32_e32 v64, v64, v65
	v_mov_b32_e32 v65, v64
	s_nop 1
	v_permlane16_swap_b32_e32 v64, v65
	v_add_f32_e32 v64, v64, v65
	v_mov_b32_e32 v65, v64
	s_nop 1
	v_permlane32_swap_b32_e32 v64, v65
	v_add_f32_e32 v64, v64, v65
	v_fmamk_f32 v64, v64, 0x3a800000, v159
	v_mul_f32_e32 v65, 0x4b800000, v64
	v_cmp_gt_f32_e32 vcc, s49, v64
	v_lshl_add_u64 v[66:67], v[138:139], 0, v[72:73]
	s_nop 0
	v_cndmask_b32_e32 v64, v64, v65, vcc
	v_rsq_f32_e32 v69, v64
	v_lshl_add_u64 v[64:65], v[70:71], 0, s[12:13]
	v_lshl_add_u64 v[64:65], v[64:65], 0, v[136:137]
	v_mul_f32_e32 v70, 0x45800000, v69
	v_cndmask_b32_e32 v70, v69, v70, vcc
	v_pk_mul_f32 v[62:63], v[62:63], v[70:71] op_sel_hi:[1,0]
	v_pk_mul_f32 v[60:61], v[60:61], v[70:71] op_sel_hi:[1,0]
	v_pk_mul_f32 v[58:59], v[58:59], v[70:71] op_sel_hi:[1,0]
	v_pk_mul_f32 v[56:57], v[56:57], v[70:71] op_sel_hi:[1,0]
	v_pk_mul_f32 v[54:55], v[54:55], v[70:71] op_sel_hi:[1,0]
	v_pk_mul_f32 v[52:53], v[52:53], v[70:71] op_sel_hi:[1,0]
	v_pk_mul_f32 v[50:51], v[50:51], v[70:71] op_sel_hi:[1,0]
	v_pk_mul_f32 v[48:49], v[48:49], v[70:71] op_sel_hi:[1,0]
	v_mul_f32_e32 v69, 0xbfb8aa3b, v60
	v_mul_f32_e32 v70, 0xbfb8aa3b, v61
	v_mul_f32_e32 v71, 0xbfb8aa3b, v62
	v_mul_f32_e32 v72, 0xbfb8aa3b, v63
	v_mul_f32_e32 v73, 0xbfb8aa3b, v56
	v_mul_f32_e32 v74, 0xbfb8aa3b, v57
	v_mul_f32_e32 v75, 0xbfb8aa3b, v58
	v_mul_f32_e32 v76, 0xbfb8aa3b, v59
	v_exp_f32_e32 v69, v69
	v_exp_f32_e32 v70, v70
	v_exp_f32_e32 v71, v71
	v_exp_f32_e32 v72, v72
	v_exp_f32_e32 v73, v73
	v_exp_f32_e32 v74, v74
	v_exp_f32_e32 v75, v75
	v_exp_f32_e32 v76, v76
	v_add_f32_e32 v69, 1.0, v69
	v_add_f32_e32 v77, 1.0, v70
	v_add_f32_e32 v78, 1.0, v71
	v_add_f32_e32 v79, 1.0, v72
	v_add_f32_e32 v80, 1.0, v73
	v_add_f32_e32 v81, 1.0, v74
	v_add_f32_e32 v82, 1.0, v75
	v_add_f32_e32 v83, 1.0, v76
	v_rcp_f32_e32 v70, v69
	v_rcp_f32_e32 v71, v77
	v_rcp_f32_e32 v72, v78
	v_rcp_f32_e32 v73, v79
	v_rcp_f32_e32 v74, v80
	v_rcp_f32_e32 v75, v81
	v_rcp_f32_e32 v76, v82
	v_rcp_f32_e32 v77, v83
	v_pk_mul_f32 v[60:61], v[60:61], v[70:71]
	v_pk_mul_f32 v[62:63], v[62:63], v[72:73]
	v_pk_mul_f32 v[56:57], v[56:57], v[74:75]
	v_pk_mul_f32 v[58:59], v[58:59], v[76:77]
	v_pk_mul_f32 v[52:53], v[52:53], v[60:61]
	v_pk_mul_f32 v[54:55], v[54:55], v[62:63]
	v_pk_mul_f32 v[56:57], v[48:49], v[56:57]
	v_pk_mul_f32 v[58:59], v[50:51], v[58:59]
	v_cvt_pk_bf16_f32 v48, v52, v53
	v_cvt_pk_bf16_f32 v49, v54, v55
	v_cvt_pk_bf16_f32 v50, v56, v57
	v_cvt_pk_bf16_f32 v51, v58, v59
	global_store_dwordx4 v[64:65], v[48:51], off
	v_add_u32_e32 v52, 0xa0, v150
	v_ashrrev_i32_e32 v53, 31, v52
	v_lshlrev_b64 v[56:57], 6, v[52:53]
	v_mad_i64_i32 v[54:55], s[0:1], v68, s50, v[148:149]
	v_lshl_add_u64 v[54:55], v[54:55], 0, s[24:25]
	v_add_f32_e32 v48, v212, v213
	v_add_f32_e32 v49, v214, v215
	v_add_f32_e32 v48, v48, v49
	v_mov_b32_e32 v49, v48
	s_nop 1
	v_permlane16_swap_b32_e32 v48, v49
	v_add_f32_e32 v48, v48, v49
	v_mov_b32_e32 v49, v48
	s_nop 1
	v_permlane32_swap_b32_e32 v48, v49
	v_add_f32_e32 v48, v48, v49
	v_fmamk_f32 v48, v48, 0x3a800000, v159
	v_mul_f32_e32 v49, 0x4b800000, v48
	v_cmp_gt_f32_e32 vcc, s49, v48
	v_lshl_add_u64 v[50:51], v[138:139], 0, v[56:57]
	s_nop 0
	v_cndmask_b32_e32 v48, v48, v49, vcc
	v_rsq_f32_e32 v53, v48
	v_lshl_add_u64 v[48:49], v[54:55], 0, s[12:13]
	v_lshl_add_u64 v[48:49], v[48:49], 0, v[136:137]
	v_mul_f32_e32 v54, 0x45800000, v53
	v_cndmask_b32_e32 v54, v53, v54, vcc
	v_pk_mul_f32 v[46:47], v[46:47], v[54:55] op_sel_hi:[1,0]
	v_pk_mul_f32 v[44:45], v[44:45], v[54:55] op_sel_hi:[1,0]
	v_pk_mul_f32 v[42:43], v[42:43], v[54:55] op_sel_hi:[1,0]
	v_pk_mul_f32 v[40:41], v[40:41], v[54:55] op_sel_hi:[1,0]
	v_pk_mul_f32 v[38:39], v[38:39], v[54:55] op_sel_hi:[1,0]
	v_pk_mul_f32 v[36:37], v[36:37], v[54:55] op_sel_hi:[1,0]
	v_pk_mul_f32 v[34:35], v[34:35], v[54:55] op_sel_hi:[1,0]
	v_pk_mul_f32 v[32:33], v[32:33], v[54:55] op_sel_hi:[1,0]
	v_mul_f32_e32 v53, 0xbfb8aa3b, v44
	v_mul_f32_e32 v54, 0xbfb8aa3b, v45
	v_mul_f32_e32 v55, 0xbfb8aa3b, v46
	v_mul_f32_e32 v56, 0xbfb8aa3b, v47
	v_mul_f32_e32 v57, 0xbfb8aa3b, v40
	v_mul_f32_e32 v58, 0xbfb8aa3b, v41
	v_mul_f32_e32 v59, 0xbfb8aa3b, v42
	v_mul_f32_e32 v60, 0xbfb8aa3b, v43
	v_exp_f32_e32 v53, v53
	v_exp_f32_e32 v54, v54
	v_exp_f32_e32 v55, v55
	v_exp_f32_e32 v56, v56
	v_exp_f32_e32 v57, v57
	v_exp_f32_e32 v58, v58
	v_exp_f32_e32 v59, v59
	v_exp_f32_e32 v60, v60
	v_add_f32_e32 v53, 1.0, v53
	v_add_f32_e32 v61, 1.0, v54
	v_add_f32_e32 v62, 1.0, v55
	v_add_f32_e32 v63, 1.0, v56
	v_add_f32_e32 v64, 1.0, v57
	v_add_f32_e32 v65, 1.0, v58
	v_add_f32_e32 v66, 1.0, v59
	v_add_f32_e32 v67, 1.0, v60
	v_rcp_f32_e32 v54, v53
	v_rcp_f32_e32 v55, v61
	v_rcp_f32_e32 v56, v62
	v_rcp_f32_e32 v57, v63
	v_rcp_f32_e32 v58, v64
	v_rcp_f32_e32 v59, v65
	v_rcp_f32_e32 v60, v66
	v_rcp_f32_e32 v61, v67
	v_pk_mul_f32 v[44:45], v[44:45], v[54:55]
	v_pk_mul_f32 v[46:47], v[46:47], v[56:57]
	v_pk_mul_f32 v[40:41], v[40:41], v[58:59]
	v_pk_mul_f32 v[42:43], v[42:43], v[60:61]
	v_pk_mul_f32 v[36:37], v[36:37], v[44:45]
	v_pk_mul_f32 v[38:39], v[38:39], v[46:47]
	v_pk_mul_f32 v[40:41], v[32:33], v[40:41]
	v_pk_mul_f32 v[42:43], v[34:35], v[42:43]
	v_cvt_pk_bf16_f32 v32, v36, v37
	v_cvt_pk_bf16_f32 v33, v38, v39
	v_cvt_pk_bf16_f32 v34, v40, v41
	v_cvt_pk_bf16_f32 v35, v42, v43
	global_store_dwordx4 v[48:49], v[32:35], off
	v_add_u32_e32 v36, 0xb0, v150
	v_ashrrev_i32_e32 v37, 31, v36
	v_lshlrev_b64 v[40:41], 6, v[36:37]
	v_mad_i64_i32 v[38:39], s[0:1], v52, s50, v[148:149]
	v_lshl_add_u64 v[38:39], v[38:39], 0, s[24:25]
	v_add_f32_e32 v32, v216, v217
	v_add_f32_e32 v33, v218, v219
	v_add_f32_e32 v32, v32, v33
	v_mov_b32_e32 v33, v32
	s_nop 1
	v_permlane16_swap_b32_e32 v32, v33
	v_add_f32_e32 v32, v32, v33
	v_mov_b32_e32 v33, v32
	s_nop 1
	v_permlane32_swap_b32_e32 v32, v33
	v_add_f32_e32 v32, v32, v33
	v_fmamk_f32 v32, v32, 0x3a800000, v159
	v_mul_f32_e32 v33, 0x4b800000, v32
	v_cmp_gt_f32_e32 vcc, s49, v32
	v_lshl_add_u64 v[34:35], v[138:139], 0, v[40:41]
	s_nop 0
	v_cndmask_b32_e32 v32, v32, v33, vcc
	v_rsq_f32_e32 v37, v32
	v_lshl_add_u64 v[32:33], v[38:39], 0, s[12:13]
	v_lshl_add_u64 v[32:33], v[32:33], 0, v[136:137]
	v_mul_f32_e32 v38, 0x45800000, v37
	v_cndmask_b32_e32 v38, v37, v38, vcc
	v_pk_mul_f32 v[30:31], v[30:31], v[38:39] op_sel_hi:[1,0]
	v_pk_mul_f32 v[28:29], v[28:29], v[38:39] op_sel_hi:[1,0]
	v_pk_mul_f32 v[26:27], v[26:27], v[38:39] op_sel_hi:[1,0]
	v_pk_mul_f32 v[24:25], v[24:25], v[38:39] op_sel_hi:[1,0]
	v_pk_mul_f32 v[22:23], v[22:23], v[38:39] op_sel_hi:[1,0]
	v_pk_mul_f32 v[20:21], v[20:21], v[38:39] op_sel_hi:[1,0]
	v_pk_mul_f32 v[18:19], v[18:19], v[38:39] op_sel_hi:[1,0]
	v_pk_mul_f32 v[16:17], v[16:17], v[38:39] op_sel_hi:[1,0]
	v_mul_f32_e32 v37, 0xbfb8aa3b, v28
	v_mul_f32_e32 v38, 0xbfb8aa3b, v29
	v_mul_f32_e32 v39, 0xbfb8aa3b, v30
	v_mul_f32_e32 v40, 0xbfb8aa3b, v31
	v_mul_f32_e32 v41, 0xbfb8aa3b, v24
	v_mul_f32_e32 v42, 0xbfb8aa3b, v25
	v_mul_f32_e32 v43, 0xbfb8aa3b, v26
	v_mul_f32_e32 v44, 0xbfb8aa3b, v27
	v_exp_f32_e32 v37, v37
	v_exp_f32_e32 v38, v38
	v_exp_f32_e32 v39, v39
	v_exp_f32_e32 v40, v40
	v_exp_f32_e32 v41, v41
	v_exp_f32_e32 v42, v42
	v_exp_f32_e32 v43, v43
	v_exp_f32_e32 v44, v44
	v_add_f32_e32 v37, 1.0, v37
	v_add_f32_e32 v45, 1.0, v38
	v_add_f32_e32 v46, 1.0, v39
	v_add_f32_e32 v47, 1.0, v40
	v_add_f32_e32 v48, 1.0, v41
	v_add_f32_e32 v49, 1.0, v42
	v_add_f32_e32 v50, 1.0, v43
	v_add_f32_e32 v51, 1.0, v44
	v_rcp_f32_e32 v38, v37
	v_rcp_f32_e32 v39, v45
	v_rcp_f32_e32 v40, v46
	v_rcp_f32_e32 v41, v47
	v_rcp_f32_e32 v42, v48
	v_rcp_f32_e32 v43, v49
	v_rcp_f32_e32 v44, v50
	v_rcp_f32_e32 v45, v51
	v_pk_mul_f32 v[28:29], v[28:29], v[38:39]
	v_pk_mul_f32 v[30:31], v[30:31], v[40:41]
	v_pk_mul_f32 v[24:25], v[24:25], v[42:43]
	v_pk_mul_f32 v[26:27], v[26:27], v[44:45]
	v_pk_mul_f32 v[20:21], v[20:21], v[28:29]
	v_pk_mul_f32 v[22:23], v[22:23], v[30:31]
	v_pk_mul_f32 v[24:25], v[16:17], v[24:25]
	v_pk_mul_f32 v[26:27], v[18:19], v[26:27]
	v_cvt_pk_bf16_f32 v16, v20, v21
	v_cvt_pk_bf16_f32 v17, v22, v23
	v_cvt_pk_bf16_f32 v18, v24, v25
	v_cvt_pk_bf16_f32 v19, v26, v27
	global_store_dwordx4 v[32:33], v[16:19], off
	v_mad_i64_i32 v[20:21], s[0:1], v36, s50, v[148:149]
	s_andn2_b64 vcc, exec, s[2:3]
	v_add_f32_e32 v16, v220, v221
	v_add_f32_e32 v17, v222, v223
	v_add_f32_e32 v16, v16, v17
	v_mov_b32_e32 v17, v16
	s_nop 1
	v_permlane16_swap_b32_e32 v16, v17
	v_add_f32_e32 v16, v16, v17
	v_mov_b32_e32 v17, v16
	s_nop 1
	v_permlane32_swap_b32_e32 v16, v17
	v_add_f32_e32 v16, v16, v17
	v_fmamk_f32 v16, v16, 0x3a800000, v159
	v_mul_f32_e32 v17, 0x4b800000, v16
	v_cmp_gt_f32_e64 s[0:1], s49, v16
	s_nop 1
	v_cndmask_b32_e64 v16, v16, v17, s[0:1]
	v_rsq_f32_e32 v18, v16
	v_lshl_add_u64 v[16:17], v[20:21], 0, s[24:25]
	v_lshl_add_u64 v[16:17], v[16:17], 0, s[12:13]
	v_lshl_add_u64 v[16:17], v[16:17], 0, v[136:137]
	v_mul_f32_e32 v19, 0x45800000, v18
	v_cndmask_b32_e64 v18, v18, v19, s[0:1]
	v_pk_mul_f32 v[14:15], v[14:15], v[18:19] op_sel_hi:[1,0]
	v_pk_mul_f32 v[12:13], v[12:13], v[18:19] op_sel_hi:[1,0]
	v_pk_mul_f32 v[10:11], v[10:11], v[18:19] op_sel_hi:[1,0]
	v_pk_mul_f32 v[8:9], v[8:9], v[18:19] op_sel_hi:[1,0]
	v_pk_mul_f32 v[6:7], v[6:7], v[18:19] op_sel_hi:[1,0]
	v_pk_mul_f32 v[4:5], v[4:5], v[18:19] op_sel_hi:[1,0]
	v_pk_mul_f32 v[2:3], v[2:3], v[18:19] op_sel_hi:[1,0]
	v_pk_mul_f32 v[0:1], v[0:1], v[18:19] op_sel_hi:[1,0]
	v_mul_f32_e32 v18, 0xbfb8aa3b, v12
	v_mul_f32_e32 v19, 0xbfb8aa3b, v13
	v_mul_f32_e32 v20, 0xbfb8aa3b, v14
	v_mul_f32_e32 v21, 0xbfb8aa3b, v15
	v_mul_f32_e32 v22, 0xbfb8aa3b, v8
	v_mul_f32_e32 v23, 0xbfb8aa3b, v9
	v_mul_f32_e32 v24, 0xbfb8aa3b, v10
	v_mul_f32_e32 v25, 0xbfb8aa3b, v11
	v_exp_f32_e32 v18, v18
	v_exp_f32_e32 v19, v19
	v_exp_f32_e32 v20, v20
	v_exp_f32_e32 v21, v21
	v_exp_f32_e32 v22, v22
	v_exp_f32_e32 v23, v23
	v_exp_f32_e32 v24, v24
	v_exp_f32_e32 v25, v25
	v_add_f32_e32 v18, 1.0, v18
	v_add_f32_e32 v19, 1.0, v19
	v_add_f32_e32 v20, 1.0, v20
	v_add_f32_e32 v21, 1.0, v21
	v_add_f32_e32 v22, 1.0, v22
	v_add_f32_e32 v23, 1.0, v23
	v_add_f32_e32 v24, 1.0, v24
	v_add_f32_e32 v25, 1.0, v25
	v_rcp_f32_e32 v18, v18
	v_rcp_f32_e32 v19, v19
	v_rcp_f32_e32 v20, v20
	v_rcp_f32_e32 v21, v21
	v_rcp_f32_e32 v22, v22
	v_rcp_f32_e32 v23, v23
	v_rcp_f32_e32 v24, v24
	v_rcp_f32_e32 v25, v25
	v_pk_mul_f32 v[12:13], v[12:13], v[18:19]
	v_pk_mul_f32 v[14:15], v[14:15], v[20:21]
	v_pk_mul_f32 v[8:9], v[8:9], v[22:23]
	v_pk_mul_f32 v[10:11], v[10:11], v[24:25]
	v_pk_mul_f32 v[4:5], v[4:5], v[12:13]
	v_pk_mul_f32 v[6:7], v[6:7], v[14:15]
	v_pk_mul_f32 v[8:9], v[0:1], v[8:9]
	v_pk_mul_f32 v[10:11], v[2:3], v[10:11]
	v_cvt_pk_bf16_f32 v0, v4, v5
	v_cvt_pk_bf16_f32 v1, v6, v7
	v_cvt_pk_bf16_f32 v2, v8, v9
	v_cvt_pk_bf16_f32 v3, v10, v11
	s_mov_b64 s[0:1], -1
	global_store_dwordx4 v[16:17], v[0:3], off
	s_cbranch_vccnz .LBB0_2649
	s_andn2_b64 vcc, exec, s[6:7]
	s_cbranch_vccnz .LBB0_2648
	s_barrier
	s_branch .LBB0_2648
